# v19 plus one static s_setprio 1 for waves 0-3 at start of attention phases 2 and 10
# speedup vs baseline: 1.0099x; 1.0099x over previous
; #define IN(k) (PH_EN(k) && lo <= (k) && (k) < hi)
;     const bf16_t* QK = (const bf16_t*)(p.ws + WS_BIG); const bf16_t* VT = (const bf16_t*)(p.ws + WS_VT); bf16_t* O = (bf16_t*)(p.ws + WS_XN);
;     const float d1 = wave_sum(p.in[5][lane] * p.in[6][lane]), d2 = wave_sum(p.in[7][lane] * p.in[8][lane]);
;     const float lam = expf(d1) - expf(d2) + 0.2f;
; __global__ void __launch_bounds__(512) trunk_fwd(Params p) {
;     ...
;     if (IN(2)) {
; #pragma nounroll
;         for (int rep = 0; rep < (PROBE_DUP == 2 ? 2 : 1); ++rep) phase_attn0(p, lds, wave, lane, rep);
.LBB0_302:
	s_add_u32 s58, s80, 0x3400000
	s_addc_u32 s59, s81, 0
	s_cmp_gt_i32 s82, 2
	s_cselect_b64 s[0:1], -1, 0
	s_cmp_lt_i32 s83, 3
	s_cselect_b64 s[2:3], -1, 0
	s_or_b64 s[0:1], s[0:1], s[2:3]
	s_and_b64 vcc, exec, s[0:1]
	s_cbranch_vccnz .LBB0_410
	v_readfirstlane_b32 s32, v177
	s_nop 3
	s_lshr_b32 s32, s32, 6
	s_cmp_lt_u32 s32, 4
	s_cbranch_scc0 .Lprio_p2_done
	s_setprio 1

; #define IN(k) (PH_EN(k) && lo <= (k) && (k) < hi)
;     const bf16_t* P1 = (const bf16_t*)(p.ws + WS_BIG); const bf16_t* VT1 = (const bf16_t*)(p.ws + WS_VT);
;     const bf16_t* KC = (const bf16_t*)(p.ws + WS_KC); const bf16_t* VCT = (const bf16_t*)(p.ws + WS_VCT); bf16_t* O = (bf16_t*)(p.ws + WS_XN);
;     unsigned* qctr = (unsigned*)(p.ws + WS_QCTR) + 8 + rep;
;     volatile unsigned* qidx = (volatile unsigned*)(lds + NS_BASE + 2 * NS_BUF);
;     for (;;) {
;         if (threadIdx.x == 0) qidx[0] = atomicAdd(qctr, 1u);
; __global__ void __launch_bounds__(512) trunk_fwd(Params p) {
;     ...
;     if (IN(10)) {
; #pragma nounroll
;         for (int rep = 0; rep < (PROBE_DUP == 10 ? 2 : 1); ++rep) phase_nsa(p, lds, wave, lane, rep);
.LBB0_962:
	s_cmp_gt_i32 s82, 10
	s_cselect_b64 s[0:1], -1, 0
	s_cmp_lt_i32 s83, 11
	s_cselect_b64 s[2:3], -1, 0
	s_or_b64 s[0:1], s[0:1], s[2:3]
	s_and_b64 vcc, exec, s[0:1]
	s_cbranch_vccnz .LBB0_1134
	v_readfirstlane_b32 s32, v177
	s_nop 3
	s_lshr_b32 s32, s32, 6
	s_cmp_lt_u32 s32, 4
	s_cbranch_scc0 .Lprio_p10_done
	s_setprio 1
